# saddr-form LDS-DMA also in out-proj / w_o / kvq GEMM loops; KZ MFMA order in all 12 loops
# baseline (speedup 1.0000x reference)
.LBB0_1009:
	ds_read_b128 v[142:145], v155
	ds_read_b128 v[158:161], v155 offset:1024
	ds_read_b128 v[168:171], v155 offset:2048
	ds_read_b128 v[176:179], v155 offset:3072
	ds_read_b128 v[180:183], v156
	ds_read_b128 v[184:187], v156 offset:1024
	ds_read_b128 v[188:191], v156 offset:2048
	ds_read_b128 v[192:195], v156 offset:3072
	s_add_u32 s24, s22, 0xfff00080
	s_addc_u32 s25, s23, -1
	s_cmp_eq_u32 s51, 60
	s_cselect_b32 s27, s19, s25
	s_cselect_b32 s26, s47, s24
	s_cselect_b32 s25, s7, s50
	s_cselect_b32 s24, s48, s49
	s_mov_b32 m0, s40
	ds_read_b128 v[202:205], v157
	ds_read_b128 v[206:209], v157 offset:1024
	ds_read_b128 v[210:213], v157 offset:2048
	ds_read_b128 v[214:217], v157 offset:3072
	ds_read_b128 v[218:221], v157 offset:4096
	ds_read_b128 v[222:225], v157 offset:5120
	ds_read_b128 v[226:229], v157 offset:6144
	ds_read_b128 v[230:233], v157 offset:7168
	global_load_lds_dwordx4 v138, s[22:23]
	s_mov_b32 m0, s41
	s_nop 0
	global_load_lds_dwordx4 v140, s[22:23]
	s_waitcnt vmcnt(8)
	s_waitcnt lgkmcnt(0)
	s_barrier
	s_setprio 1
	s_waitcnt lgkmcnt(0)
	v_mfma_f32_16x16x32_bf16 v[126:129], v[142:145], v[202:205], v[126:129]
	v_mfma_f32_16x16x32_bf16 v[126:129], v[158:161], v[206:209], v[126:129]
	v_mfma_f32_16x16x32_bf16 v[122:125], v[176:179], v[206:209], v[122:125]
	v_mfma_f32_16x16x32_bf16 v[122:125], v[168:171], v[202:205], v[122:125]
	v_mfma_f32_16x16x32_bf16 v[106:109], v[168:171], v[210:213], v[106:109]
	v_mfma_f32_16x16x32_bf16 v[106:109], v[176:179], v[214:217], v[106:109]
	v_mfma_f32_16x16x32_bf16 v[110:113], v[158:161], v[214:217], v[110:113]
	v_mfma_f32_16x16x32_bf16 v[110:113], v[142:145], v[210:213], v[110:113]
	v_mfma_f32_16x16x32_bf16 v[94:97], v[142:145], v[218:221], v[94:97]
	v_mfma_f32_16x16x32_bf16 v[94:97], v[158:161], v[222:225], v[94:97]
	v_mfma_f32_16x16x32_bf16 v[90:93], v[176:179], v[222:225], v[90:93]
	v_mfma_f32_16x16x32_bf16 v[90:93], v[168:171], v[218:221], v[90:93]
	v_mfma_f32_16x16x32_bf16 v[74:77], v[168:171], v[226:229], v[74:77]
	v_mfma_f32_16x16x32_bf16 v[74:77], v[176:179], v[230:233], v[74:77]
	v_mfma_f32_16x16x32_bf16 v[78:81], v[158:161], v[230:233], v[78:81]
	v_mfma_f32_16x16x32_bf16 v[78:81], v[142:145], v[226:229], v[78:81]
	v_mfma_f32_16x16x32_bf16 v[70:73], v[180:183], v[226:229], v[70:73]
	v_mfma_f32_16x16x32_bf16 v[70:73], v[184:187], v[230:233], v[70:73]
	v_mfma_f32_16x16x32_bf16 v[66:69], v[192:195], v[230:233], v[66:69]
	v_mfma_f32_16x16x32_bf16 v[66:69], v[188:191], v[226:229], v[66:69]
	v_mfma_f32_16x16x32_bf16 v[82:85], v[188:191], v[218:221], v[82:85]
	v_mfma_f32_16x16x32_bf16 v[82:85], v[192:195], v[222:225], v[82:85]
	v_mfma_f32_16x16x32_bf16 v[86:89], v[184:187], v[222:225], v[86:89]
	v_mfma_f32_16x16x32_bf16 v[86:89], v[180:183], v[218:221], v[86:89]
	v_mfma_f32_16x16x32_bf16 v[102:105], v[180:183], v[210:213], v[102:105]
	v_mfma_f32_16x16x32_bf16 v[102:105], v[184:187], v[214:217], v[102:105]
	v_mfma_f32_16x16x32_bf16 v[98:101], v[192:195], v[214:217], v[98:101]
	v_mfma_f32_16x16x32_bf16 v[98:101], v[188:191], v[210:213], v[98:101]
	v_mfma_f32_16x16x32_bf16 v[114:117], v[188:191], v[202:205], v[114:117]
	v_mfma_f32_16x16x32_bf16 v[114:117], v[192:195], v[206:209], v[114:117]
	v_mfma_f32_16x16x32_bf16 v[118:121], v[184:187], v[206:209], v[118:121]
	v_mfma_f32_16x16x32_bf16 v[118:121], v[180:183], v[202:205], v[118:121]
	s_setprio 0
	s_barrier
	s_mov_b32 m0, s42
	s_add_u32 s52, s24, 0x100000
	ds_read_b128 v[202:205], v157 offset:16384
	ds_read_b128 v[206:209], v157 offset:17408
	ds_read_b128 v[210:213], v157 offset:18432
	ds_read_b128 v[214:217], v157 offset:19456
	ds_read_b128 v[218:221], v157 offset:20480
	ds_read_b128 v[222:225], v157 offset:21504
	ds_read_b128 v[226:229], v157 offset:22528
	ds_read_b128 v[230:233], v157 offset:23552
	global_load_lds_dwordx4 v132, s[24:25]
	s_mov_b32 m0, s43
	s_addc_u32 s53, s25, 0
	global_load_lds_dwordx4 v136, s[24:25]
	s_mov_b32 m0, s44
	s_nop 0
	global_load_lds_dwordx4 v132, s[52:53]
	s_add_i32 m0, s44, 0x2000
	s_nop 0
	global_load_lds_dwordx4 v136, s[52:53]
	s_mov_b32 m0, s33
	s_nop 0
	global_load_lds_dwordx4 v130, s[26:27]
	s_mov_b32 m0, s34
	s_nop 0
	global_load_lds_dwordx4 v134, s[26:27]
	s_waitcnt vmcnt(8)
	s_waitcnt lgkmcnt(0)
	s_barrier
	s_setprio 1
	s_waitcnt lgkmcnt(0)
	v_mfma_f32_16x16x32_bf16 v[62:65], v[142:145], v[202:205], v[62:65]
	v_mfma_f32_16x16x32_bf16 v[62:65], v[158:161], v[206:209], v[62:65]
	v_mfma_f32_16x16x32_bf16 v[58:61], v[176:179], v[206:209], v[58:61]
	v_mfma_f32_16x16x32_bf16 v[58:61], v[168:171], v[202:205], v[58:61]
	v_mfma_f32_16x16x32_bf16 v[42:45], v[168:171], v[210:213], v[42:45]
	v_mfma_f32_16x16x32_bf16 v[42:45], v[176:179], v[214:217], v[42:45]
	v_mfma_f32_16x16x32_bf16 v[46:49], v[158:161], v[214:217], v[46:49]
	v_mfma_f32_16x16x32_bf16 v[46:49], v[142:145], v[210:213], v[46:49]
	v_mfma_f32_16x16x32_bf16 v[30:33], v[142:145], v[218:221], v[30:33]
	v_mfma_f32_16x16x32_bf16 v[30:33], v[158:161], v[222:225], v[30:33]
	v_mfma_f32_16x16x32_bf16 v[26:29], v[176:179], v[222:225], v[26:29]
	v_mfma_f32_16x16x32_bf16 v[26:29], v[168:171], v[218:221], v[26:29]
	v_mfma_f32_16x16x32_bf16 v[10:13], v[168:171], v[226:229], v[10:13]
	v_mfma_f32_16x16x32_bf16 v[10:13], v[176:179], v[230:233], v[10:13]
	v_mfma_f32_16x16x32_bf16 v[14:17], v[158:161], v[230:233], v[14:17]
	v_mfma_f32_16x16x32_bf16 v[14:17], v[142:145], v[226:229], v[14:17]
	v_mfma_f32_16x16x32_bf16 v[6:9], v[180:183], v[226:229], v[6:9]
	v_mfma_f32_16x16x32_bf16 v[6:9], v[184:187], v[230:233], v[6:9]
	v_mfma_f32_16x16x32_bf16 v[2:5], v[192:195], v[230:233], v[2:5]
	v_mfma_f32_16x16x32_bf16 v[2:5], v[188:191], v[226:229], v[2:5]
	v_mfma_f32_16x16x32_bf16 v[18:21], v[188:191], v[218:221], v[18:21]
	v_mfma_f32_16x16x32_bf16 v[18:21], v[192:195], v[222:225], v[18:21]
	v_mfma_f32_16x16x32_bf16 v[22:25], v[184:187], v[222:225], v[22:25]
	v_mfma_f32_16x16x32_bf16 v[22:25], v[180:183], v[218:221], v[22:25]
	v_mfma_f32_16x16x32_bf16 v[38:41], v[180:183], v[210:213], v[38:41]
	v_mfma_f32_16x16x32_bf16 v[38:41], v[184:187], v[214:217], v[38:41]
	v_mfma_f32_16x16x32_bf16 v[34:37], v[192:195], v[214:217], v[34:37]
	v_mfma_f32_16x16x32_bf16 v[34:37], v[188:191], v[210:213], v[34:37]
	v_mfma_f32_16x16x32_bf16 v[50:53], v[188:191], v[202:205], v[50:53]
	v_mfma_f32_16x16x32_bf16 v[50:53], v[192:195], v[206:209], v[50:53]
	v_mfma_f32_16x16x32_bf16 v[54:57], v[184:187], v[206:209], v[54:57]
	v_mfma_f32_16x16x32_bf16 v[54:57], v[180:183], v[202:205], v[54:57]
	s_setprio 0
	s_barrier
	s_add_i32 s52, 0, 0x18000
	v_add_u32_e32 v166, s52, v153
	s_add_i32 s53, 0, 0x1c000
	ds_read_b128 v[142:145], v166
	ds_read_b128 v[158:161], v166 offset:1024
	ds_read_b128 v[168:171], v166 offset:2048
	ds_read_b128 v[176:179], v166 offset:3072
	v_add_u32_e32 v166, s53, v153
	ds_read_b128 v[180:183], v166
	ds_read_b128 v[184:187], v166 offset:1024
	ds_read_b128 v[188:191], v166 offset:2048
	ds_read_b128 v[192:195], v166 offset:3072
	s_add_u32 s26, s26, 0x100000
	s_addc_u32 s27, s27, 0
	s_mov_b32 m0, s35
	ds_read_b128 v[202:205], v157 offset:32768
	ds_read_b128 v[206:209], v157 offset:33792
	ds_read_b128 v[210:213], v157 offset:34816
	ds_read_b128 v[214:217], v157 offset:35840
	ds_read_b128 v[218:221], v157 offset:36864
	ds_read_b128 v[222:225], v157 offset:37888
	ds_read_b128 v[226:229], v157 offset:38912
	ds_read_b128 v[230:233], v157 offset:39936
	global_load_lds_dwordx4 v130, s[26:27]
	s_mov_b32 m0, s36
	s_nop 0
	global_load_lds_dwordx4 v134, s[26:27]
	s_waitcnt vmcnt(8)
	s_waitcnt lgkmcnt(0)
	s_barrier
	s_setprio 1
	s_waitcnt lgkmcnt(0)
	v_mfma_f32_16x16x32_bf16 v[126:129], v[142:145], v[202:205], v[126:129]
	v_mfma_f32_16x16x32_bf16 v[126:129], v[158:161], v[206:209], v[126:129]
	v_mfma_f32_16x16x32_bf16 v[122:125], v[176:179], v[206:209], v[122:125]
	v_mfma_f32_16x16x32_bf16 v[122:125], v[168:171], v[202:205], v[122:125]
	v_mfma_f32_16x16x32_bf16 v[106:109], v[168:171], v[210:213], v[106:109]
	v_mfma_f32_16x16x32_bf16 v[106:109], v[176:179], v[214:217], v[106:109]
	v_mfma_f32_16x16x32_bf16 v[110:113], v[158:161], v[214:217], v[110:113]
	v_mfma_f32_16x16x32_bf16 v[110:113], v[142:145], v[210:213], v[110:113]
	v_mfma_f32_16x16x32_bf16 v[94:97], v[142:145], v[218:221], v[94:97]
	v_mfma_f32_16x16x32_bf16 v[94:97], v[158:161], v[222:225], v[94:97]
	v_mfma_f32_16x16x32_bf16 v[90:93], v[176:179], v[222:225], v[90:93]
	v_mfma_f32_16x16x32_bf16 v[90:93], v[168:171], v[218:221], v[90:93]
	v_mfma_f32_16x16x32_bf16 v[74:77], v[168:171], v[226:229], v[74:77]
	v_mfma_f32_16x16x32_bf16 v[74:77], v[176:179], v[230:233], v[74:77]
	v_mfma_f32_16x16x32_bf16 v[78:81], v[158:161], v[230:233], v[78:81]
	v_mfma_f32_16x16x32_bf16 v[78:81], v[142:145], v[226:229], v[78:81]
	v_mfma_f32_16x16x32_bf16 v[70:73], v[180:183], v[226:229], v[70:73]
	v_mfma_f32_16x16x32_bf16 v[70:73], v[184:187], v[230:233], v[70:73]
	v_mfma_f32_16x16x32_bf16 v[66:69], v[192:195], v[230:233], v[66:69]
	v_mfma_f32_16x16x32_bf16 v[66:69], v[188:191], v[226:229], v[66:69]
	v_mfma_f32_16x16x32_bf16 v[82:85], v[188:191], v[218:221], v[82:85]
	v_mfma_f32_16x16x32_bf16 v[82:85], v[192:195], v[222:225], v[82:85]
	v_mfma_f32_16x16x32_bf16 v[86:89], v[184:187], v[222:225], v[86:89]
	v_mfma_f32_16x16x32_bf16 v[86:89], v[180:183], v[218:221], v[86:89]
	v_mfma_f32_16x16x32_bf16 v[102:105], v[180:183], v[210:213], v[102:105]
	v_mfma_f32_16x16x32_bf16 v[102:105], v[184:187], v[214:217], v[102:105]
	v_mfma_f32_16x16x32_bf16 v[98:101], v[192:195], v[214:217], v[98:101]
	v_mfma_f32_16x16x32_bf16 v[98:101], v[188:191], v[210:213], v[98:101]
	v_mfma_f32_16x16x32_bf16 v[114:117], v[188:191], v[202:205], v[114:117]
	v_mfma_f32_16x16x32_bf16 v[114:117], v[192:195], v[206:209], v[114:117]
	v_mfma_f32_16x16x32_bf16 v[118:121], v[184:187], v[206:209], v[118:121]
	v_mfma_f32_16x16x32_bf16 v[118:121], v[180:183], v[202:205], v[118:121]
	s_setprio 0
	s_barrier
	s_add_u32 s98, s26, 0xfff00080
	s_addc_u32 s99, s27, -1
	s_add_u32 s24, s24, 0x80
	s_addc_u32 s25, s25, 0
	s_add_i32 s26, s52, s30
	s_mov_b32 m0, s26
	ds_read_b128 v[202:205], v157 offset:49152
	ds_read_b128 v[206:209], v157 offset:50176
	ds_read_b128 v[210:213], v157 offset:51200
	ds_read_b128 v[214:217], v157 offset:52224
	ds_read_b128 v[218:221], v157 offset:53248
	ds_read_b128 v[222:225], v157 offset:54272
	ds_read_b128 v[226:229], v157 offset:55296
	ds_read_b128 v[230:233], v157 offset:56320
	global_load_lds_dwordx4 v132, s[24:25]
	s_add_i32 m0, s26, 0x2000
	s_add_i32 s26, s53, s30
	global_load_lds_dwordx4 v136, s[24:25]
	s_add_u32 s24, s24, 0x100000
	s_addc_u32 s25, s25, 0
	s_mov_b32 m0, s26
	s_nop 0
	global_load_lds_dwordx4 v132, s[24:25]
	s_add_i32 m0, s26, 0x2000
	s_nop 0
	global_load_lds_dwordx4 v136, s[24:25]
	s_mov_b32 m0, s38
	s_nop 0
	global_load_lds_dwordx4 v130, s[98:99]
	s_mov_b32 m0, s39
	s_nop 0
	global_load_lds_dwordx4 v134, s[98:99]
	s_waitcnt vmcnt(8)
	s_waitcnt lgkmcnt(0)
	s_barrier
	s_setprio 1
	s_waitcnt lgkmcnt(0)
	v_mfma_f32_16x16x32_bf16 v[62:65], v[142:145], v[202:205], v[62:65]
	v_mfma_f32_16x16x32_bf16 v[62:65], v[158:161], v[206:209], v[62:65]
	v_mfma_f32_16x16x32_bf16 v[58:61], v[176:179], v[206:209], v[58:61]
	v_mfma_f32_16x16x32_bf16 v[58:61], v[168:171], v[202:205], v[58:61]
	v_mfma_f32_16x16x32_bf16 v[42:45], v[168:171], v[210:213], v[42:45]
	v_mfma_f32_16x16x32_bf16 v[42:45], v[176:179], v[214:217], v[42:45]
	v_mfma_f32_16x16x32_bf16 v[46:49], v[158:161], v[214:217], v[46:49]
	v_mfma_f32_16x16x32_bf16 v[46:49], v[142:145], v[210:213], v[46:49]
	v_mfma_f32_16x16x32_bf16 v[30:33], v[142:145], v[218:221], v[30:33]
	v_mfma_f32_16x16x32_bf16 v[30:33], v[158:161], v[222:225], v[30:33]
	v_mfma_f32_16x16x32_bf16 v[26:29], v[176:179], v[222:225], v[26:29]
	v_mfma_f32_16x16x32_bf16 v[26:29], v[168:171], v[218:221], v[26:29]
	v_mfma_f32_16x16x32_bf16 v[10:13], v[168:171], v[226:229], v[10:13]
	v_mfma_f32_16x16x32_bf16 v[10:13], v[176:179], v[230:233], v[10:13]
	v_mfma_f32_16x16x32_bf16 v[14:17], v[158:161], v[230:233], v[14:17]
	v_mfma_f32_16x16x32_bf16 v[14:17], v[142:145], v[226:229], v[14:17]
	v_mfma_f32_16x16x32_bf16 v[6:9], v[180:183], v[226:229], v[6:9]
	v_mfma_f32_16x16x32_bf16 v[6:9], v[184:187], v[230:233], v[6:9]
	v_mfma_f32_16x16x32_bf16 v[2:5], v[192:195], v[230:233], v[2:5]
	v_mfma_f32_16x16x32_bf16 v[2:5], v[188:191], v[226:229], v[2:5]
	v_mfma_f32_16x16x32_bf16 v[18:21], v[188:191], v[218:221], v[18:21]
	v_mfma_f32_16x16x32_bf16 v[18:21], v[192:195], v[222:225], v[18:21]
	v_mfma_f32_16x16x32_bf16 v[22:25], v[184:187], v[222:225], v[22:25]
	v_mfma_f32_16x16x32_bf16 v[22:25], v[180:183], v[218:221], v[22:25]
	v_mfma_f32_16x16x32_bf16 v[38:41], v[180:183], v[210:213], v[38:41]
	v_mfma_f32_16x16x32_bf16 v[38:41], v[184:187], v[214:217], v[38:41]
	v_mfma_f32_16x16x32_bf16 v[34:37], v[192:195], v[214:217], v[34:37]
	v_mfma_f32_16x16x32_bf16 v[34:37], v[188:191], v[210:213], v[34:37]
	v_mfma_f32_16x16x32_bf16 v[50:53], v[188:191], v[202:205], v[50:53]
	v_mfma_f32_16x16x32_bf16 v[50:53], v[192:195], v[206:209], v[50:53]
	v_mfma_f32_16x16x32_bf16 v[54:57], v[184:187], v[206:209], v[54:57]
	v_mfma_f32_16x16x32_bf16 v[54:57], v[180:183], v[202:205], v[54:57]
	s_setprio 0
	s_barrier
	s_add_i32 s51, s51, 2
	s_add_u32 s22, s22, 0x100
	s_addc_u32 s23, s23, 0
	s_add_u32 s49, s49, 0x100
	s_addc_u32 s50, s50, 0
	s_cmp_gt_u32 s51, 61
	s_cbranch_scc0 .LBB0_1009
	s_and_b64 vcc, exec, s[16:17]
	s_cbranch_vccz .LBB0_1012
	s_barrier

.LBB0_1565:
	ds_read_b128 v[130:133], v204
	ds_read_b128 v[134:137], v204 offset:1024
	ds_read_b128 v[138:141], v204 offset:2048
	ds_read_b128 v[142:145], v204 offset:3072
	ds_read_b128 v[146:149], v205
	ds_read_b128 v[150:153], v205 offset:1024
	ds_read_b128 v[154:157], v205 offset:2048
	ds_read_b128 v[158:161], v205 offset:3072
	s_add_u32 s8, s6, 0xfff00080
	s_addc_u32 s9, s7, -1
	s_cmp_eq_u32 s66, 60
	s_cselect_b32 s73, s41, s9
	s_cselect_b32 s72, s50, s8
	s_cselect_b32 s9, s13, s57
	s_cselect_b32 s8, s51, s56
	s_add_i32 m0, s42, 0xc000
	ds_read_b128 v[184:187], v206
	ds_read_b128 v[188:191], v206 offset:1024
	ds_read_b128 v[192:195], v206 offset:2048
	ds_read_b128 v[210:213], v206 offset:3072
	ds_read_b128 v[214:217], v206 offset:4096
	ds_read_b128 v[218:221], v206 offset:5120
	ds_read_b128 v[222:225], v206 offset:6144
	ds_read_b128 v[226:229], v206 offset:7168
	global_load_lds_dwordx4 v180, s[6:7]
	s_add_i32 m0, s42, 0xe000
	s_nop 0
	global_load_lds_dwordx4 v182, s[6:7]
	s_waitcnt vmcnt(8)
	s_waitcnt lgkmcnt(0)
	s_barrier
	s_setprio 1
	s_waitcnt lgkmcnt(0)
	v_mfma_f32_16x16x32_bf16 v[126:129], v[130:133], v[184:187], v[126:129]
	v_mfma_f32_16x16x32_bf16 v[126:129], v[134:137], v[188:191], v[126:129]
	v_mfma_f32_16x16x32_bf16 v[122:125], v[142:145], v[188:191], v[122:125]
	v_mfma_f32_16x16x32_bf16 v[122:125], v[138:141], v[184:187], v[122:125]
	v_mfma_f32_16x16x32_bf16 v[106:109], v[138:141], v[192:195], v[106:109]
	v_mfma_f32_16x16x32_bf16 v[106:109], v[142:145], v[210:213], v[106:109]
	v_mfma_f32_16x16x32_bf16 v[110:113], v[134:137], v[210:213], v[110:113]
	v_mfma_f32_16x16x32_bf16 v[110:113], v[130:133], v[192:195], v[110:113]
	v_mfma_f32_16x16x32_bf16 v[94:97], v[130:133], v[214:217], v[94:97]
	v_mfma_f32_16x16x32_bf16 v[94:97], v[134:137], v[218:221], v[94:97]
	v_mfma_f32_16x16x32_bf16 v[90:93], v[142:145], v[218:221], v[90:93]
	v_mfma_f32_16x16x32_bf16 v[90:93], v[138:141], v[214:217], v[90:93]
	v_mfma_f32_16x16x32_bf16 v[74:77], v[138:141], v[222:225], v[74:77]
	v_mfma_f32_16x16x32_bf16 v[74:77], v[142:145], v[226:229], v[74:77]
	v_mfma_f32_16x16x32_bf16 v[78:81], v[134:137], v[226:229], v[78:81]
	v_mfma_f32_16x16x32_bf16 v[78:81], v[130:133], v[222:225], v[78:81]
	v_mfma_f32_16x16x32_bf16 v[70:73], v[146:149], v[222:225], v[70:73]
	v_mfma_f32_16x16x32_bf16 v[70:73], v[150:153], v[226:229], v[70:73]
	v_mfma_f32_16x16x32_bf16 v[66:69], v[158:161], v[226:229], v[66:69]
	v_mfma_f32_16x16x32_bf16 v[66:69], v[154:157], v[222:225], v[66:69]
	v_mfma_f32_16x16x32_bf16 v[82:85], v[154:157], v[214:217], v[82:85]
	v_mfma_f32_16x16x32_bf16 v[82:85], v[158:161], v[218:221], v[82:85]
	v_mfma_f32_16x16x32_bf16 v[86:89], v[150:153], v[218:221], v[86:89]
	v_mfma_f32_16x16x32_bf16 v[86:89], v[146:149], v[214:217], v[86:89]
	v_mfma_f32_16x16x32_bf16 v[102:105], v[146:149], v[192:195], v[102:105]
	v_mfma_f32_16x16x32_bf16 v[102:105], v[150:153], v[210:213], v[102:105]
	v_mfma_f32_16x16x32_bf16 v[98:101], v[158:161], v[210:213], v[98:101]
	v_mfma_f32_16x16x32_bf16 v[98:101], v[154:157], v[192:195], v[98:101]
	v_mfma_f32_16x16x32_bf16 v[114:117], v[154:157], v[184:187], v[114:117]
	v_mfma_f32_16x16x32_bf16 v[114:117], v[158:161], v[188:191], v[114:117]
	v_mfma_f32_16x16x32_bf16 v[118:121], v[150:153], v[188:191], v[118:121]
	v_mfma_f32_16x16x32_bf16 v[118:121], v[146:149], v[184:187], v[118:121]
	s_setprio 0
	s_barrier
	s_add_i32 s67, s54, s35
	s_mov_b32 m0, s67
	ds_read_b128 v[184:187], v206 offset:16384
	ds_read_b128 v[188:191], v206 offset:17408
	ds_read_b128 v[192:195], v206 offset:18432
	ds_read_b128 v[210:213], v206 offset:19456
	ds_read_b128 v[214:217], v206 offset:20480
	ds_read_b128 v[218:221], v206 offset:21504
	ds_read_b128 v[222:225], v206 offset:22528
	ds_read_b128 v[226:229], v206 offset:23552
	global_load_lds_dwordx4 v168, s[8:9]
	s_add_i32 m0, s67, 0x2000
	s_add_u32 s68, s8, 0x100000
	s_addc_u32 s69, s9, 0
	s_add_i32 s67, s55, s35
	global_load_lds_dwordx4 v170, s[8:9]
	s_mov_b32 m0, s67
	s_nop 0
	global_load_lds_dwordx4 v168, s[68:69]
	s_add_i32 m0, s67, 0x2000
	s_nop 0
	global_load_lds_dwordx4 v170, s[68:69]
	s_mov_b32 m0, s42
	s_nop 0
	global_load_lds_dwordx4 v168, s[72:73]
	s_mov_b32 m0, s43
	s_nop 0
	global_load_lds_dwordx4 v170, s[72:73]
	s_waitcnt vmcnt(8)
	s_waitcnt lgkmcnt(0)
	s_barrier
	s_setprio 1
	s_waitcnt lgkmcnt(0)
	v_mfma_f32_16x16x32_bf16 v[62:65], v[130:133], v[184:187], v[62:65]
	v_mfma_f32_16x16x32_bf16 v[62:65], v[134:137], v[188:191], v[62:65]
	v_mfma_f32_16x16x32_bf16 v[58:61], v[142:145], v[188:191], v[58:61]
	v_mfma_f32_16x16x32_bf16 v[58:61], v[138:141], v[184:187], v[58:61]
	v_mfma_f32_16x16x32_bf16 v[42:45], v[138:141], v[192:195], v[42:45]
	v_mfma_f32_16x16x32_bf16 v[42:45], v[142:145], v[210:213], v[42:45]
	v_mfma_f32_16x16x32_bf16 v[46:49], v[134:137], v[210:213], v[46:49]
	v_mfma_f32_16x16x32_bf16 v[46:49], v[130:133], v[192:195], v[46:49]
	v_mfma_f32_16x16x32_bf16 v[30:33], v[130:133], v[214:217], v[30:33]
	v_mfma_f32_16x16x32_bf16 v[30:33], v[134:137], v[218:221], v[30:33]
	v_mfma_f32_16x16x32_bf16 v[26:29], v[142:145], v[218:221], v[26:29]
	v_mfma_f32_16x16x32_bf16 v[26:29], v[138:141], v[214:217], v[26:29]
	v_mfma_f32_16x16x32_bf16 v[10:13], v[138:141], v[222:225], v[10:13]
	v_mfma_f32_16x16x32_bf16 v[10:13], v[142:145], v[226:229], v[10:13]
	v_mfma_f32_16x16x32_bf16 v[14:17], v[134:137], v[226:229], v[14:17]
	v_mfma_f32_16x16x32_bf16 v[14:17], v[130:133], v[222:225], v[14:17]
	v_mfma_f32_16x16x32_bf16 v[6:9], v[146:149], v[222:225], v[6:9]
	v_mfma_f32_16x16x32_bf16 v[6:9], v[150:153], v[226:229], v[6:9]
	v_mfma_f32_16x16x32_bf16 v[2:5], v[158:161], v[226:229], v[2:5]
	v_mfma_f32_16x16x32_bf16 v[2:5], v[154:157], v[222:225], v[2:5]
	v_mfma_f32_16x16x32_bf16 v[18:21], v[154:157], v[214:217], v[18:21]
	v_mfma_f32_16x16x32_bf16 v[18:21], v[158:161], v[218:221], v[18:21]
	v_mfma_f32_16x16x32_bf16 v[22:25], v[150:153], v[218:221], v[22:25]
	v_mfma_f32_16x16x32_bf16 v[22:25], v[146:149], v[214:217], v[22:25]
	v_mfma_f32_16x16x32_bf16 v[38:41], v[146:149], v[192:195], v[38:41]
	v_mfma_f32_16x16x32_bf16 v[38:41], v[150:153], v[210:213], v[38:41]
	v_mfma_f32_16x16x32_bf16 v[34:37], v[158:161], v[210:213], v[34:37]
	v_mfma_f32_16x16x32_bf16 v[34:37], v[154:157], v[192:195], v[34:37]
	v_mfma_f32_16x16x32_bf16 v[50:53], v[154:157], v[184:187], v[50:53]
	v_mfma_f32_16x16x32_bf16 v[50:53], v[158:161], v[188:191], v[50:53]
	v_mfma_f32_16x16x32_bf16 v[54:57], v[150:153], v[188:191], v[54:57]
	v_mfma_f32_16x16x32_bf16 v[54:57], v[146:149], v[184:187], v[54:57]
	s_setprio 0
	s_barrier
	s_add_i32 s67, 0, 0x18000
	s_add_i32 s70, 0, 0x1c000
	v_add_u32_e32 v142, s67, v203
	v_add_u32_e32 v158, s70, v203
	ds_read_b128 v[130:133], v142
	ds_read_b128 v[134:137], v142 offset:1024
	ds_read_b128 v[138:141], v142 offset:2048
	ds_read_b128 v[142:145], v142 offset:3072
	ds_read_b128 v[146:149], v158
	ds_read_b128 v[150:153], v158 offset:1024
	ds_read_b128 v[154:157], v158 offset:2048
	ds_read_b128 v[158:161], v158 offset:3072
	s_add_u32 s68, s72, 0x100000
	s_addc_u32 s69, s73, 0
	s_mov_b32 m0, s44
	ds_read_b128 v[184:187], v206 offset:32768
	ds_read_b128 v[188:191], v206 offset:33792
	ds_read_b128 v[192:195], v206 offset:34816
	ds_read_b128 v[210:213], v206 offset:35840
	ds_read_b128 v[214:217], v206 offset:36864
	ds_read_b128 v[218:221], v206 offset:37888
	ds_read_b128 v[222:225], v206 offset:38912
	ds_read_b128 v[226:229], v206 offset:39936
	global_load_lds_dwordx4 v168, s[68:69]
	s_mov_b32 m0, s45
	s_nop 0
	global_load_lds_dwordx4 v170, s[68:69]
	s_waitcnt vmcnt(8)
	s_waitcnt lgkmcnt(0)
	s_barrier
	s_setprio 1
	s_waitcnt lgkmcnt(0)
	v_mfma_f32_16x16x32_bf16 v[126:129], v[130:133], v[184:187], v[126:129]
	v_mfma_f32_16x16x32_bf16 v[126:129], v[134:137], v[188:191], v[126:129]
	v_mfma_f32_16x16x32_bf16 v[122:125], v[142:145], v[188:191], v[122:125]
	v_mfma_f32_16x16x32_bf16 v[122:125], v[138:141], v[184:187], v[122:125]
	v_mfma_f32_16x16x32_bf16 v[106:109], v[138:141], v[192:195], v[106:109]
	v_mfma_f32_16x16x32_bf16 v[106:109], v[142:145], v[210:213], v[106:109]
	v_mfma_f32_16x16x32_bf16 v[110:113], v[134:137], v[210:213], v[110:113]
	v_mfma_f32_16x16x32_bf16 v[110:113], v[130:133], v[192:195], v[110:113]
	v_mfma_f32_16x16x32_bf16 v[94:97], v[130:133], v[214:217], v[94:97]
	v_mfma_f32_16x16x32_bf16 v[94:97], v[134:137], v[218:221], v[94:97]
	v_mfma_f32_16x16x32_bf16 v[90:93], v[142:145], v[218:221], v[90:93]
	v_mfma_f32_16x16x32_bf16 v[90:93], v[138:141], v[214:217], v[90:93]
	v_mfma_f32_16x16x32_bf16 v[74:77], v[138:141], v[222:225], v[74:77]
	v_mfma_f32_16x16x32_bf16 v[74:77], v[142:145], v[226:229], v[74:77]
	v_mfma_f32_16x16x32_bf16 v[78:81], v[134:137], v[226:229], v[78:81]
	v_mfma_f32_16x16x32_bf16 v[78:81], v[130:133], v[222:225], v[78:81]
	v_mfma_f32_16x16x32_bf16 v[70:73], v[146:149], v[222:225], v[70:73]
	v_mfma_f32_16x16x32_bf16 v[70:73], v[150:153], v[226:229], v[70:73]
	v_mfma_f32_16x16x32_bf16 v[66:69], v[158:161], v[226:229], v[66:69]
	v_mfma_f32_16x16x32_bf16 v[66:69], v[154:157], v[222:225], v[66:69]
	v_mfma_f32_16x16x32_bf16 v[82:85], v[154:157], v[214:217], v[82:85]
	v_mfma_f32_16x16x32_bf16 v[82:85], v[158:161], v[218:221], v[82:85]
	v_mfma_f32_16x16x32_bf16 v[86:89], v[150:153], v[218:221], v[86:89]
	v_mfma_f32_16x16x32_bf16 v[86:89], v[146:149], v[214:217], v[86:89]
	v_mfma_f32_16x16x32_bf16 v[102:105], v[146:149], v[192:195], v[102:105]
	v_mfma_f32_16x16x32_bf16 v[102:105], v[150:153], v[210:213], v[102:105]
	v_mfma_f32_16x16x32_bf16 v[98:101], v[158:161], v[210:213], v[98:101]
	v_mfma_f32_16x16x32_bf16 v[98:101], v[154:157], v[192:195], v[98:101]
	v_mfma_f32_16x16x32_bf16 v[114:117], v[154:157], v[184:187], v[114:117]
	v_mfma_f32_16x16x32_bf16 v[114:117], v[158:161], v[188:191], v[114:117]
	v_mfma_f32_16x16x32_bf16 v[118:121], v[150:153], v[188:191], v[118:121]
	v_mfma_f32_16x16x32_bf16 v[118:121], v[146:149], v[184:187], v[118:121]
	s_setprio 0
	s_barrier
	s_add_u32 s68, s72, 0x80
	s_addc_u32 s69, s73, 0
	s_add_u32 s8, s8, 0x80
	s_addc_u32 s9, s9, 0
	s_add_i32 s67, s67, s35
	s_mov_b32 m0, s67
	ds_read_b128 v[184:187], v206 offset:49152
	ds_read_b128 v[188:191], v206 offset:50176
	ds_read_b128 v[192:195], v206 offset:51200
	ds_read_b128 v[210:213], v206 offset:52224
	ds_read_b128 v[214:217], v206 offset:53248
	ds_read_b128 v[218:221], v206 offset:54272
	ds_read_b128 v[222:225], v206 offset:55296
	ds_read_b128 v[226:229], v206 offset:56320
	global_load_lds_dwordx4 v168, s[8:9]
	s_add_i32 m0, s67, 0x2000
	s_add_i32 s67, s70, s35
	global_load_lds_dwordx4 v170, s[8:9]
	s_add_u32 s8, s8, 0x100000
	s_addc_u32 s9, s9, 0
	s_mov_b32 m0, s67
	s_nop 0
	global_load_lds_dwordx4 v168, s[8:9]
	s_add_i32 m0, s67, 0x2000
	s_nop 0
	global_load_lds_dwordx4 v170, s[8:9]
	s_mov_b32 m0, s48
	s_nop 0
	global_load_lds_dwordx4 v168, s[68:69]
	s_mov_b32 m0, s49
	s_nop 0
	global_load_lds_dwordx4 v170, s[68:69]
	s_waitcnt vmcnt(8)
	s_waitcnt lgkmcnt(0)
	s_barrier
	s_setprio 1
	s_waitcnt lgkmcnt(0)
	v_mfma_f32_16x16x32_bf16 v[62:65], v[130:133], v[184:187], v[62:65]
	v_mfma_f32_16x16x32_bf16 v[62:65], v[134:137], v[188:191], v[62:65]
	v_mfma_f32_16x16x32_bf16 v[58:61], v[142:145], v[188:191], v[58:61]
	v_mfma_f32_16x16x32_bf16 v[58:61], v[138:141], v[184:187], v[58:61]
	v_mfma_f32_16x16x32_bf16 v[42:45], v[138:141], v[192:195], v[42:45]
	v_mfma_f32_16x16x32_bf16 v[42:45], v[142:145], v[210:213], v[42:45]
	v_mfma_f32_16x16x32_bf16 v[46:49], v[134:137], v[210:213], v[46:49]
	v_mfma_f32_16x16x32_bf16 v[46:49], v[130:133], v[192:195], v[46:49]
	v_mfma_f32_16x16x32_bf16 v[30:33], v[130:133], v[214:217], v[30:33]
	v_mfma_f32_16x16x32_bf16 v[30:33], v[134:137], v[218:221], v[30:33]
	v_mfma_f32_16x16x32_bf16 v[26:29], v[142:145], v[218:221], v[26:29]
	v_mfma_f32_16x16x32_bf16 v[26:29], v[138:141], v[214:217], v[26:29]
	v_mfma_f32_16x16x32_bf16 v[10:13], v[138:141], v[222:225], v[10:13]
	v_mfma_f32_16x16x32_bf16 v[10:13], v[142:145], v[226:229], v[10:13]
	v_mfma_f32_16x16x32_bf16 v[14:17], v[134:137], v[226:229], v[14:17]
	v_mfma_f32_16x16x32_bf16 v[14:17], v[130:133], v[222:225], v[14:17]
	v_mfma_f32_16x16x32_bf16 v[6:9], v[146:149], v[222:225], v[6:9]
	v_mfma_f32_16x16x32_bf16 v[6:9], v[150:153], v[226:229], v[6:9]
	v_mfma_f32_16x16x32_bf16 v[2:5], v[158:161], v[226:229], v[2:5]
	v_mfma_f32_16x16x32_bf16 v[2:5], v[154:157], v[222:225], v[2:5]
	v_mfma_f32_16x16x32_bf16 v[18:21], v[154:157], v[214:217], v[18:21]
	v_mfma_f32_16x16x32_bf16 v[18:21], v[158:161], v[218:221], v[18:21]
	v_mfma_f32_16x16x32_bf16 v[22:25], v[150:153], v[218:221], v[22:25]
	v_mfma_f32_16x16x32_bf16 v[22:25], v[146:149], v[214:217], v[22:25]
	v_mfma_f32_16x16x32_bf16 v[38:41], v[146:149], v[192:195], v[38:41]
	v_mfma_f32_16x16x32_bf16 v[38:41], v[150:153], v[210:213], v[38:41]
	v_mfma_f32_16x16x32_bf16 v[34:37], v[158:161], v[210:213], v[34:37]
	v_mfma_f32_16x16x32_bf16 v[34:37], v[154:157], v[192:195], v[34:37]
	v_mfma_f32_16x16x32_bf16 v[50:53], v[154:157], v[184:187], v[50:53]
	v_mfma_f32_16x16x32_bf16 v[50:53], v[158:161], v[188:191], v[50:53]
	v_mfma_f32_16x16x32_bf16 v[54:57], v[150:153], v[188:191], v[54:57]
	v_mfma_f32_16x16x32_bf16 v[54:57], v[146:149], v[184:187], v[54:57]
	s_setprio 0
	s_barrier
	s_add_i32 s66, s66, 2
	s_add_u32 s6, s6, 0x100
	s_addc_u32 s7, s7, 0
	s_add_u32 s56, s56, 0x100
	s_addc_u32 s57, s57, 0
	s_cmp_gt_u32 s66, 61
	s_cbranch_scc0 .LBB0_1565
	s_and_b64 vcc, exec, s[24:25]
	s_cbranch_vccz .LBB0_1568
	s_barrier

.LBB0_2230:
	ds_read_b128 v[142:145], v154
	ds_read_b128 v[158:161], v154 offset:1024
	ds_read_b128 v[168:171], v154 offset:2048
	ds_read_b128 v[176:179], v154 offset:3072
	ds_read_b128 v[180:183], v155
	ds_read_b128 v[184:187], v155 offset:1024
	ds_read_b128 v[188:191], v155 offset:2048
	ds_read_b128 v[192:195], v155 offset:3072
	s_add_u32 s24, s22, 0xfff00080
	s_addc_u32 s25, s23, -1
	s_cmp_eq_u32 s48, 60
	s_cselect_b32 s27, s19, s25
	s_cselect_b32 s26, s44, s24
	s_cselect_b32 s25, s7, s47
	s_cselect_b32 s24, s45, s46
	s_mov_b32 m0, s40
	ds_read_b128 v[204:207], v156
	ds_read_b128 v[208:211], v156 offset:1024
	ds_read_b128 v[212:215], v156 offset:2048
	ds_read_b128 v[216:219], v156 offset:3072
	ds_read_b128 v[220:223], v156 offset:4096
	ds_read_b128 v[224:227], v156 offset:5120
	ds_read_b128 v[228:231], v156 offset:6144
	ds_read_b128 v[232:235], v156 offset:7168
	global_load_lds_dwordx4 v138, s[22:23]
	s_mov_b32 m0, s41
	s_nop 0
	global_load_lds_dwordx4 v140, s[22:23]
	s_waitcnt vmcnt(8)
	s_waitcnt lgkmcnt(0)
	s_barrier
	s_setprio 1
	s_waitcnt lgkmcnt(0)
	v_mfma_f32_16x16x32_bf16 v[126:129], v[142:145], v[204:207], v[126:129]
	v_mfma_f32_16x16x32_bf16 v[126:129], v[158:161], v[208:211], v[126:129]
	v_mfma_f32_16x16x32_bf16 v[122:125], v[176:179], v[208:211], v[122:125]
	v_mfma_f32_16x16x32_bf16 v[122:125], v[168:171], v[204:207], v[122:125]
	v_mfma_f32_16x16x32_bf16 v[106:109], v[168:171], v[212:215], v[106:109]
	v_mfma_f32_16x16x32_bf16 v[106:109], v[176:179], v[216:219], v[106:109]
	v_mfma_f32_16x16x32_bf16 v[110:113], v[158:161], v[216:219], v[110:113]
	v_mfma_f32_16x16x32_bf16 v[110:113], v[142:145], v[212:215], v[110:113]
	v_mfma_f32_16x16x32_bf16 v[94:97], v[142:145], v[220:223], v[94:97]
	v_mfma_f32_16x16x32_bf16 v[94:97], v[158:161], v[224:227], v[94:97]
	v_mfma_f32_16x16x32_bf16 v[90:93], v[176:179], v[224:227], v[90:93]
	v_mfma_f32_16x16x32_bf16 v[90:93], v[168:171], v[220:223], v[90:93]
	v_mfma_f32_16x16x32_bf16 v[74:77], v[168:171], v[228:231], v[74:77]
	v_mfma_f32_16x16x32_bf16 v[74:77], v[176:179], v[232:235], v[74:77]
	v_mfma_f32_16x16x32_bf16 v[78:81], v[158:161], v[232:235], v[78:81]
	v_mfma_f32_16x16x32_bf16 v[78:81], v[142:145], v[228:231], v[78:81]
	v_mfma_f32_16x16x32_bf16 v[70:73], v[180:183], v[228:231], v[70:73]
	v_mfma_f32_16x16x32_bf16 v[70:73], v[184:187], v[232:235], v[70:73]
	v_mfma_f32_16x16x32_bf16 v[66:69], v[192:195], v[232:235], v[66:69]
	v_mfma_f32_16x16x32_bf16 v[66:69], v[188:191], v[228:231], v[66:69]
	v_mfma_f32_16x16x32_bf16 v[82:85], v[188:191], v[220:223], v[82:85]
	v_mfma_f32_16x16x32_bf16 v[82:85], v[192:195], v[224:227], v[82:85]
	v_mfma_f32_16x16x32_bf16 v[86:89], v[184:187], v[224:227], v[86:89]
	v_mfma_f32_16x16x32_bf16 v[86:89], v[180:183], v[220:223], v[86:89]
	v_mfma_f32_16x16x32_bf16 v[102:105], v[180:183], v[212:215], v[102:105]
	v_mfma_f32_16x16x32_bf16 v[102:105], v[184:187], v[216:219], v[102:105]
	v_mfma_f32_16x16x32_bf16 v[98:101], v[192:195], v[216:219], v[98:101]
	v_mfma_f32_16x16x32_bf16 v[98:101], v[188:191], v[212:215], v[98:101]
	v_mfma_f32_16x16x32_bf16 v[114:117], v[188:191], v[204:207], v[114:117]
	v_mfma_f32_16x16x32_bf16 v[114:117], v[192:195], v[208:211], v[114:117]
	v_mfma_f32_16x16x32_bf16 v[118:121], v[184:187], v[208:211], v[118:121]
	v_mfma_f32_16x16x32_bf16 v[118:121], v[180:183], v[204:207], v[118:121]
	s_setprio 0
	s_barrier
	s_add_i32 s49, s38, s28
	s_mov_b32 m0, s49
	ds_read_b128 v[204:207], v156 offset:16384
	ds_read_b128 v[208:211], v156 offset:17408
	ds_read_b128 v[212:215], v156 offset:18432
	ds_read_b128 v[216:219], v156 offset:19456
	ds_read_b128 v[220:223], v156 offset:20480
	ds_read_b128 v[224:227], v156 offset:21504
	ds_read_b128 v[228:231], v156 offset:22528
	ds_read_b128 v[232:235], v156 offset:23552
	global_load_lds_dwordx4 v132, s[24:25]
	s_add_i32 m0, s49, 0x2000
	s_add_u32 s50, s24, 0x100000
	s_addc_u32 s51, s25, 0
	s_add_i32 s49, s39, s28
	global_load_lds_dwordx4 v136, s[24:25]
	s_mov_b32 m0, s49
	s_nop 0
	global_load_lds_dwordx4 v132, s[50:51]
	s_add_i32 m0, s49, 0x2000
	s_nop 0
	global_load_lds_dwordx4 v136, s[50:51]
	s_mov_b32 m0, s30
	s_nop 0
	global_load_lds_dwordx4 v130, s[26:27]
	s_mov_b32 m0, s31
	s_nop 0
	global_load_lds_dwordx4 v134, s[26:27]
	s_waitcnt vmcnt(8)
	s_waitcnt lgkmcnt(0)
	s_barrier
	s_setprio 1
	s_waitcnt lgkmcnt(0)
	v_mfma_f32_16x16x32_bf16 v[62:65], v[142:145], v[204:207], v[62:65]
	v_mfma_f32_16x16x32_bf16 v[62:65], v[158:161], v[208:211], v[62:65]
	v_mfma_f32_16x16x32_bf16 v[58:61], v[176:179], v[208:211], v[58:61]
	v_mfma_f32_16x16x32_bf16 v[58:61], v[168:171], v[204:207], v[58:61]
	v_mfma_f32_16x16x32_bf16 v[42:45], v[168:171], v[212:215], v[42:45]
	v_mfma_f32_16x16x32_bf16 v[42:45], v[176:179], v[216:219], v[42:45]
	v_mfma_f32_16x16x32_bf16 v[46:49], v[158:161], v[216:219], v[46:49]
	v_mfma_f32_16x16x32_bf16 v[46:49], v[142:145], v[212:215], v[46:49]
	v_mfma_f32_16x16x32_bf16 v[30:33], v[142:145], v[220:223], v[30:33]
	v_mfma_f32_16x16x32_bf16 v[30:33], v[158:161], v[224:227], v[30:33]
	v_mfma_f32_16x16x32_bf16 v[26:29], v[176:179], v[224:227], v[26:29]
	v_mfma_f32_16x16x32_bf16 v[26:29], v[168:171], v[220:223], v[26:29]
	v_mfma_f32_16x16x32_bf16 v[10:13], v[168:171], v[228:231], v[10:13]
	v_mfma_f32_16x16x32_bf16 v[10:13], v[176:179], v[232:235], v[10:13]
	v_mfma_f32_16x16x32_bf16 v[14:17], v[158:161], v[232:235], v[14:17]
	v_mfma_f32_16x16x32_bf16 v[14:17], v[142:145], v[228:231], v[14:17]
	v_mfma_f32_16x16x32_bf16 v[6:9], v[180:183], v[228:231], v[6:9]
	v_mfma_f32_16x16x32_bf16 v[6:9], v[184:187], v[232:235], v[6:9]
	v_mfma_f32_16x16x32_bf16 v[2:5], v[192:195], v[232:235], v[2:5]
	v_mfma_f32_16x16x32_bf16 v[2:5], v[188:191], v[228:231], v[2:5]
	v_mfma_f32_16x16x32_bf16 v[18:21], v[188:191], v[220:223], v[18:21]
	v_mfma_f32_16x16x32_bf16 v[18:21], v[192:195], v[224:227], v[18:21]
	v_mfma_f32_16x16x32_bf16 v[22:25], v[184:187], v[224:227], v[22:25]
	v_mfma_f32_16x16x32_bf16 v[22:25], v[180:183], v[220:223], v[22:25]
	v_mfma_f32_16x16x32_bf16 v[38:41], v[180:183], v[212:215], v[38:41]
	v_mfma_f32_16x16x32_bf16 v[38:41], v[184:187], v[216:219], v[38:41]
	v_mfma_f32_16x16x32_bf16 v[34:37], v[192:195], v[216:219], v[34:37]
	v_mfma_f32_16x16x32_bf16 v[34:37], v[188:191], v[212:215], v[34:37]
	v_mfma_f32_16x16x32_bf16 v[50:53], v[188:191], v[204:207], v[50:53]
	v_mfma_f32_16x16x32_bf16 v[50:53], v[192:195], v[208:211], v[50:53]
	v_mfma_f32_16x16x32_bf16 v[54:57], v[184:187], v[208:211], v[54:57]
	v_mfma_f32_16x16x32_bf16 v[54:57], v[180:183], v[204:207], v[54:57]
	s_setprio 0
	s_barrier
	s_add_i32 s49, 0, 0x18000
	v_add_u32_e32 v157, s49, v152
	s_add_i32 s50, 0, 0x1c000
	ds_read_b128 v[142:145], v157
	ds_read_b128 v[158:161], v157 offset:1024
	ds_read_b128 v[168:171], v157 offset:2048
	ds_read_b128 v[176:179], v157 offset:3072
	v_add_u32_e32 v157, s50, v152
	ds_read_b128 v[180:183], v157
	ds_read_b128 v[184:187], v157 offset:1024
	ds_read_b128 v[188:191], v157 offset:2048
	ds_read_b128 v[192:195], v157 offset:3072
	s_add_u32 s26, s26, 0x100000
	s_addc_u32 s27, s27, 0
	s_mov_b32 m0, s33
	ds_read_b128 v[204:207], v156 offset:32768
	ds_read_b128 v[208:211], v156 offset:33792
	ds_read_b128 v[212:215], v156 offset:34816
	ds_read_b128 v[216:219], v156 offset:35840
	ds_read_b128 v[220:223], v156 offset:36864
	ds_read_b128 v[224:227], v156 offset:37888
	ds_read_b128 v[228:231], v156 offset:38912
	ds_read_b128 v[232:235], v156 offset:39936
	global_load_lds_dwordx4 v130, s[26:27]
	s_mov_b32 m0, s34
	s_nop 0
	global_load_lds_dwordx4 v134, s[26:27]
	s_waitcnt vmcnt(8)
	s_waitcnt lgkmcnt(0)
	s_barrier
	s_setprio 1
	s_waitcnt lgkmcnt(0)
	v_mfma_f32_16x16x32_bf16 v[126:129], v[142:145], v[204:207], v[126:129]
	v_mfma_f32_16x16x32_bf16 v[126:129], v[158:161], v[208:211], v[126:129]
	v_mfma_f32_16x16x32_bf16 v[122:125], v[176:179], v[208:211], v[122:125]
	v_mfma_f32_16x16x32_bf16 v[122:125], v[168:171], v[204:207], v[122:125]
	v_mfma_f32_16x16x32_bf16 v[106:109], v[168:171], v[212:215], v[106:109]
	v_mfma_f32_16x16x32_bf16 v[106:109], v[176:179], v[216:219], v[106:109]
	v_mfma_f32_16x16x32_bf16 v[110:113], v[158:161], v[216:219], v[110:113]
	v_mfma_f32_16x16x32_bf16 v[110:113], v[142:145], v[212:215], v[110:113]
	v_mfma_f32_16x16x32_bf16 v[94:97], v[142:145], v[220:223], v[94:97]
	v_mfma_f32_16x16x32_bf16 v[94:97], v[158:161], v[224:227], v[94:97]
	v_mfma_f32_16x16x32_bf16 v[90:93], v[176:179], v[224:227], v[90:93]
	v_mfma_f32_16x16x32_bf16 v[90:93], v[168:171], v[220:223], v[90:93]
	v_mfma_f32_16x16x32_bf16 v[74:77], v[168:171], v[228:231], v[74:77]
	v_mfma_f32_16x16x32_bf16 v[74:77], v[176:179], v[232:235], v[74:77]
	v_mfma_f32_16x16x32_bf16 v[78:81], v[158:161], v[232:235], v[78:81]
	v_mfma_f32_16x16x32_bf16 v[78:81], v[142:145], v[228:231], v[78:81]
	v_mfma_f32_16x16x32_bf16 v[70:73], v[180:183], v[228:231], v[70:73]
	v_mfma_f32_16x16x32_bf16 v[70:73], v[184:187], v[232:235], v[70:73]
	v_mfma_f32_16x16x32_bf16 v[66:69], v[192:195], v[232:235], v[66:69]
	v_mfma_f32_16x16x32_bf16 v[66:69], v[188:191], v[228:231], v[66:69]
	v_mfma_f32_16x16x32_bf16 v[82:85], v[188:191], v[220:223], v[82:85]
	v_mfma_f32_16x16x32_bf16 v[82:85], v[192:195], v[224:227], v[82:85]
	v_mfma_f32_16x16x32_bf16 v[86:89], v[184:187], v[224:227], v[86:89]
	v_mfma_f32_16x16x32_bf16 v[86:89], v[180:183], v[220:223], v[86:89]
	v_mfma_f32_16x16x32_bf16 v[102:105], v[180:183], v[212:215], v[102:105]
	v_mfma_f32_16x16x32_bf16 v[102:105], v[184:187], v[216:219], v[102:105]
	v_mfma_f32_16x16x32_bf16 v[98:101], v[192:195], v[216:219], v[98:101]
	v_mfma_f32_16x16x32_bf16 v[98:101], v[188:191], v[212:215], v[98:101]
	v_mfma_f32_16x16x32_bf16 v[114:117], v[188:191], v[204:207], v[114:117]
	v_mfma_f32_16x16x32_bf16 v[114:117], v[192:195], v[208:211], v[114:117]
	v_mfma_f32_16x16x32_bf16 v[118:121], v[184:187], v[208:211], v[118:121]
	v_mfma_f32_16x16x32_bf16 v[118:121], v[180:183], v[204:207], v[118:121]
	s_setprio 0
	s_barrier
	s_add_u32 s98, s26, 0xfff00080
	s_addc_u32 s99, s27, -1
	s_add_u32 s24, s24, 0x80
	s_addc_u32 s25, s25, 0
	s_add_i32 s26, s49, s28
	s_mov_b32 m0, s26
	ds_read_b128 v[204:207], v156 offset:49152
	ds_read_b128 v[208:211], v156 offset:50176
	ds_read_b128 v[212:215], v156 offset:51200
	ds_read_b128 v[216:219], v156 offset:52224
	ds_read_b128 v[220:223], v156 offset:53248
	ds_read_b128 v[224:227], v156 offset:54272
	ds_read_b128 v[228:231], v156 offset:55296
	ds_read_b128 v[232:235], v156 offset:56320
	global_load_lds_dwordx4 v132, s[24:25]
	s_add_i32 m0, s26, 0x2000
	s_add_i32 s26, s50, s28
	global_load_lds_dwordx4 v136, s[24:25]
	s_add_u32 s24, s24, 0x100000
	s_addc_u32 s25, s25, 0
	s_mov_b32 m0, s26
	s_nop 0
	global_load_lds_dwordx4 v132, s[24:25]
	s_add_i32 m0, s26, 0x2000
	s_nop 0
	global_load_lds_dwordx4 v136, s[24:25]
	s_mov_b32 m0, s36
	s_nop 0
	global_load_lds_dwordx4 v130, s[98:99]
	s_mov_b32 m0, s37
	s_nop 0
	global_load_lds_dwordx4 v134, s[98:99]
	s_waitcnt vmcnt(8)
	s_waitcnt lgkmcnt(0)
	s_barrier
	s_setprio 1
	s_waitcnt lgkmcnt(0)
	v_mfma_f32_16x16x32_bf16 v[62:65], v[142:145], v[204:207], v[62:65]
	v_mfma_f32_16x16x32_bf16 v[62:65], v[158:161], v[208:211], v[62:65]
	v_mfma_f32_16x16x32_bf16 v[58:61], v[176:179], v[208:211], v[58:61]
	v_mfma_f32_16x16x32_bf16 v[58:61], v[168:171], v[204:207], v[58:61]
	v_mfma_f32_16x16x32_bf16 v[42:45], v[168:171], v[212:215], v[42:45]
	v_mfma_f32_16x16x32_bf16 v[42:45], v[176:179], v[216:219], v[42:45]
	v_mfma_f32_16x16x32_bf16 v[46:49], v[158:161], v[216:219], v[46:49]
	v_mfma_f32_16x16x32_bf16 v[46:49], v[142:145], v[212:215], v[46:49]
	v_mfma_f32_16x16x32_bf16 v[30:33], v[142:145], v[220:223], v[30:33]
	v_mfma_f32_16x16x32_bf16 v[30:33], v[158:161], v[224:227], v[30:33]
	v_mfma_f32_16x16x32_bf16 v[26:29], v[176:179], v[224:227], v[26:29]
	v_mfma_f32_16x16x32_bf16 v[26:29], v[168:171], v[220:223], v[26:29]
	v_mfma_f32_16x16x32_bf16 v[10:13], v[168:171], v[228:231], v[10:13]
	v_mfma_f32_16x16x32_bf16 v[10:13], v[176:179], v[232:235], v[10:13]
	v_mfma_f32_16x16x32_bf16 v[14:17], v[158:161], v[232:235], v[14:17]
	v_mfma_f32_16x16x32_bf16 v[14:17], v[142:145], v[228:231], v[14:17]
	v_mfma_f32_16x16x32_bf16 v[6:9], v[180:183], v[228:231], v[6:9]
	v_mfma_f32_16x16x32_bf16 v[6:9], v[184:187], v[232:235], v[6:9]
	v_mfma_f32_16x16x32_bf16 v[2:5], v[192:195], v[232:235], v[2:5]
	v_mfma_f32_16x16x32_bf16 v[2:5], v[188:191], v[228:231], v[2:5]
	v_mfma_f32_16x16x32_bf16 v[18:21], v[188:191], v[220:223], v[18:21]
	v_mfma_f32_16x16x32_bf16 v[18:21], v[192:195], v[224:227], v[18:21]
	v_mfma_f32_16x16x32_bf16 v[22:25], v[184:187], v[224:227], v[22:25]
	v_mfma_f32_16x16x32_bf16 v[22:25], v[180:183], v[220:223], v[22:25]
	v_mfma_f32_16x16x32_bf16 v[38:41], v[180:183], v[212:215], v[38:41]
	v_mfma_f32_16x16x32_bf16 v[38:41], v[184:187], v[216:219], v[38:41]
	v_mfma_f32_16x16x32_bf16 v[34:37], v[192:195], v[216:219], v[34:37]
	v_mfma_f32_16x16x32_bf16 v[34:37], v[188:191], v[212:215], v[34:37]
	v_mfma_f32_16x16x32_bf16 v[50:53], v[188:191], v[204:207], v[50:53]
	v_mfma_f32_16x16x32_bf16 v[50:53], v[192:195], v[208:211], v[50:53]
	v_mfma_f32_16x16x32_bf16 v[54:57], v[184:187], v[208:211], v[54:57]
	v_mfma_f32_16x16x32_bf16 v[54:57], v[180:183], v[204:207], v[54:57]
	s_setprio 0
	s_barrier
	s_add_i32 s48, s48, 2
	s_add_u32 s22, s22, 0x100
	s_addc_u32 s23, s23, 0
	s_add_u32 s46, s46, 0x100
	s_addc_u32 s47, s47, 0
	s_cmp_gt_u32 s48, 61
	s_cbranch_scc0 .LBB0_2230
	s_and_b64 vcc, exec, s[16:17]
	s_cbranch_vccz .LBB0_2233
	s_barrier

	.amdhsa_kernel _Z8yoco_fwd4Args
		.amdhsa_group_segment_fixed_size 0
		.amdhsa_private_segment_fixed_size 0
		.amdhsa_kernarg_size 464
		.amdhsa_user_sgpr_count 2
		.amdhsa_user_sgpr_dispatch_ptr 0
		.amdhsa_user_sgpr_queue_ptr 0
		.amdhsa_user_sgpr_kernarg_segment_ptr 1
		.amdhsa_user_sgpr_dispatch_id 0
		.amdhsa_user_sgpr_kernarg_preload_length 0
		.amdhsa_user_sgpr_kernarg_preload_offset 0
		.amdhsa_user_sgpr_private_segment_size 0
		.amdhsa_uses_dynamic_stack 0
		.amdhsa_enable_private_segment 0
		.amdhsa_system_sgpr_workgroup_id_x 1
		.amdhsa_system_sgpr_workgroup_id_y 0
		.amdhsa_system_sgpr_workgroup_id_z 0
		.amdhsa_system_sgpr_workgroup_info 0
		.amdhsa_system_vgpr_workitem_id 0
		.amdhsa_next_free_vgpr 251
		.amdhsa_next_free_sgpr 100
		.amdhsa_accum_offset 252
		.amdhsa_reserve_vcc 1
		.amdhsa_float_round_mode_32 0
		.amdhsa_float_round_mode_16_64 0
		.amdhsa_float_denorm_mode_32 3
		.amdhsa_float_denorm_mode_16_64 3
		.amdhsa_dx10_clamp 1
		.amdhsa_ieee_mode 1
		.amdhsa_fp16_overflow 0
		.amdhsa_tg_split 0
		.amdhsa_exception_fp_ieee_invalid_op 0
		.amdhsa_exception_fp_denorm_src 0
		.amdhsa_exception_fp_ieee_div_zero 0
		.amdhsa_exception_fp_ieee_overflow 0
		.amdhsa_exception_fp_ieee_underflow 0
		.amdhsa_exception_fp_ieee_inexact 0
		.amdhsa_exception_int_div_zero 0
	.end_amdhsa_kernel

amdhsa.kernels:
  - .agpr_count:     0
    .args:
      - .offset:         0
        .size:           208
        .value_kind:     by_value
      - .offset:         208
        .size:           4
        .value_kind:     hidden_block_count_x
      - .offset:         212
        .size:           4
        .value_kind:     hidden_block_count_y
      - .offset:         216
        .size:           4
        .value_kind:     hidden_block_count_z
      - .offset:         220
        .size:           2
        .value_kind:     hidden_group_size_x
      - .offset:         222
        .size:           2
        .value_kind:     hidden_group_size_y
      - .offset:         224
        .size:           2
        .value_kind:     hidden_group_size_z
      - .offset:         226
        .size:           2
        .value_kind:     hidden_remainder_x
      - .offset:         228
        .size:           2
        .value_kind:     hidden_remainder_y
      - .offset:         230
        .size:           2
        .value_kind:     hidden_remainder_z
      - .offset:         248
        .size:           8
        .value_kind:     hidden_global_offset_x
      - .offset:         256
        .size:           8
        .value_kind:     hidden_global_offset_y
      - .offset:         264
        .size:           8
        .value_kind:     hidden_global_offset_z
      - .offset:         272
        .size:           2
        .value_kind:     hidden_grid_dims
      - .offset:         328
        .size:           4
        .value_kind:     hidden_dynamic_lds_size
    .group_segment_fixed_size: 0
    .kernarg_segment_align: 8
    .kernarg_segment_size: 464
    .language:       OpenCL C
    .language_version:
      - 2
      - 0
    .max_flat_workgroup_size: 512
    .name:           _Z8yoco_fwd4Args
    .private_segment_fixed_size: 0
    .sgpr_count:     106
    .sgpr_spill_count: 304
    .symbol:         _Z8yoco_fwd4Args.kd
    .uniform_work_group_size: 1
    .uses_dynamic_stack: false
    .vgpr_count:     251
    .vgpr_spill_count: 0
    .wavefront_size: 64
